# LRU serial scan rewritten: per-direction straight-line code with immediate-offset LDS addressing (3 instructions per step instead of ~10)
# baseline (speedup 1.0000x reference)
.LBB0_942:
	v_add_f32_e32 v92, v123, v92
	v_mul_f32_e32 v92, 0xbfb8aa3b, v92
	v_exp_f32_e32 v92, v92
	s_waitcnt lgkmcnt(0)
	s_barrier
	v_add_f32_e32 v92, 1.0, v92
	v_rcp_f32_e32 v92, v92
	s_nop 0
	v_mul_f32_e32 v92, 0xc1000000, v92
	v_mul_f32_e32 v92, v127, v92
	v_mul_f32_e32 v224, -2.0, v92
	v_cmp_ngt_f32_e32 vcc, s76, v224
	s_and_saveexec_b64 s[0:1], vcc
	s_xor_b64 s[0:1], exec, s[0:1]
	v_mul_f32_e32 v223, 0xbfb8aa3b, v224
	v_exp_f32_e32 v223, v223
	s_nop 0
	v_sub_f32_e32 v223, 1.0, v223
	s_andn2_saveexec_b64 s[0:1], s[0:1]
	v_fmamk_f32 v223, v224, 0xbab60b61, v192
	v_fmaak_f32 v223, v224, v223, 0xbd2aaaab
	v_fmaak_f32 v223, v224, v223, 0x3e2aaaab
	v_fma_f32 v223, v224, v223, -0.5
	v_fma_f32 v223, v224, v223, 1.0
	v_mul_f32_e32 v223, v224, v223
	s_or_b64 exec, exec, s[0:1]
	v_add_f32_e32 v88, v125, v88
	v_mul_f32_e32 v88, 0xbfb8aa3b, v88
	v_exp_f32_e32 v88, v88
	v_add_f32_e32 v93, v123, v93
	v_mul_f32_e32 v93, 0xbfb8aa3b, v93
	v_exp_f32_e32 v93, v93
	v_max_f32_e32 v223, v223, v223
	v_add_f32_e32 v88, 1.0, v88
	v_rcp_f32_e32 v88, v88
	v_max_f32_e32 v223, 0, v223
	v_mul_f32_e32 v92, 0x3fb8aa3b, v92
	v_sqrt_f32_e32 v223, v223
	v_add_f32_e32 v93, 1.0, v93
	v_exp_f32_e32 v92, v92
	v_rcp_f32_e32 v93, v93
	v_lshlrev_b32_e32 v222, 16, v222
	v_mul_f32_e32 v88, v88, v222
	v_mul_f32_e32 v88, v88, v223
	ds_write2st64_b32 v117, v92, v88 offset1:128
	v_mul_f32_e32 v88, 0xc1000000, v93
	v_mul_f32_e32 v88, v127, v88
	v_mul_f32_e32 v93, -2.0, v88
	v_cmp_ngt_f32_e32 vcc, s76, v93
	s_and_saveexec_b64 s[0:1], vcc
	s_xor_b64 s[0:1], exec, s[0:1]
	v_mul_f32_e32 v92, 0xbfb8aa3b, v93
	v_exp_f32_e32 v92, v92
	s_nop 0
	v_sub_f32_e32 v92, 1.0, v92
	s_andn2_saveexec_b64 s[0:1], s[0:1]
	v_fmamk_f32 v92, v93, 0xbab60b61, v192
	v_fmaak_f32 v92, v93, v92, 0xbd2aaaab
	v_fmaak_f32 v92, v93, v92, 0x3e2aaaab
	v_fma_f32 v92, v93, v92, -0.5
	v_fma_f32 v92, v93, v92, 1.0
	v_mul_f32_e32 v92, v93, v92
	s_or_b64 exec, exec, s[0:1]
	v_add_f32_e32 v89, v125, v89
	v_mul_f32_e32 v89, 0xbfb8aa3b, v89
	v_exp_f32_e32 v89, v89
	v_add_f32_e32 v93, v123, v94
	v_mul_f32_e32 v93, 0xbfb8aa3b, v93
	v_exp_f32_e32 v93, v93
	v_max_f32_e32 v92, v92, v92
	v_add_f32_e32 v89, 1.0, v89
	v_rcp_f32_e32 v89, v89
	v_max_f32_e32 v92, 0, v92
	v_mul_f32_e32 v88, 0x3fb8aa3b, v88
	v_sqrt_f32_e32 v92, v92
	v_add_f32_e32 v93, 1.0, v93
	v_exp_f32_e32 v88, v88
	v_rcp_f32_e32 v93, v93
	v_lshlrev_b32_e32 v94, 16, v221
	v_mul_f32_e32 v89, v89, v94
	v_mul_f32_e32 v89, v89, v92
	ds_write2st64_b32 v117, v88, v89 offset0:1 offset1:129
	v_mul_f32_e32 v88, 0xc1000000, v93
	v_mul_f32_e32 v88, v127, v88
	v_mul_f32_e32 v92, -2.0, v88
	v_cmp_ngt_f32_e32 vcc, s76, v92
	s_and_saveexec_b64 s[0:1], vcc
	s_xor_b64 s[0:1], exec, s[0:1]
	v_mul_f32_e32 v89, 0xbfb8aa3b, v92
	v_exp_f32_e32 v89, v89
	s_nop 0
	v_sub_f32_e32 v89, 1.0, v89
	s_andn2_saveexec_b64 s[0:1], s[0:1]
	v_fmamk_f32 v89, v92, 0xbab60b61, v192
	v_fmaak_f32 v89, v92, v89, 0xbd2aaaab
	v_fmaak_f32 v89, v92, v89, 0x3e2aaaab
	v_fma_f32 v89, v92, v89, -0.5
	v_fma_f32 v89, v92, v89, 1.0
	v_mul_f32_e32 v89, v92, v89
	s_or_b64 exec, exec, s[0:1]
	v_add_f32_e32 v90, v125, v90
	v_mul_f32_e32 v90, 0xbfb8aa3b, v90
	v_exp_f32_e32 v90, v90
	v_add_f32_e32 v92, v123, v95
	v_mul_f32_e32 v92, 0xbfb8aa3b, v92
	v_exp_f32_e32 v92, v92
	v_max_f32_e32 v89, v89, v89
	v_add_f32_e32 v90, 1.0, v90
	v_rcp_f32_e32 v90, v90
	v_max_f32_e32 v89, 0, v89
	v_mul_f32_e32 v88, 0x3fb8aa3b, v88
	v_sqrt_f32_e32 v89, v89
	v_add_f32_e32 v92, 1.0, v92
	v_exp_f32_e32 v88, v88
	v_rcp_f32_e32 v92, v92
	v_lshlrev_b32_e32 v93, 16, v220
	v_mul_f32_e32 v90, v90, v93
	v_mul_f32_e32 v89, v90, v89
	ds_write2st64_b32 v117, v88, v89 offset0:2 offset1:130
	v_mul_f32_e32 v88, 0xc1000000, v92
	v_mul_f32_e32 v88, v127, v88
	v_mul_f32_e32 v90, -2.0, v88
	v_cmp_ngt_f32_e32 vcc, s76, v90
	s_and_saveexec_b64 s[0:1], vcc
	s_xor_b64 s[0:1], exec, s[0:1]
	v_mul_f32_e32 v89, 0xbfb8aa3b, v90
	v_exp_f32_e32 v89, v89
	s_nop 0
	v_sub_f32_e32 v89, 1.0, v89
	s_andn2_saveexec_b64 s[0:1], s[0:1]
	v_fmamk_f32 v89, v90, 0xbab60b61, v192
	v_fmaak_f32 v89, v90, v89, 0xbd2aaaab
	v_fmaak_f32 v89, v90, v89, 0x3e2aaaab
	v_fma_f32 v89, v90, v89, -0.5
	v_fma_f32 v89, v90, v89, 1.0
	v_mul_f32_e32 v89, v90, v89
	s_or_b64 exec, exec, s[0:1]
	v_add_f32_e32 v90, v125, v91
	v_add_f32_e32 v84, v123, v84
	v_mul_f32_e32 v90, 0xbfb8aa3b, v90
	v_mul_f32_e32 v84, 0xbfb8aa3b, v84
	v_exp_f32_e32 v90, v90
	v_exp_f32_e32 v84, v84
	v_max_f32_e32 v89, v89, v89
	v_max_f32_e32 v89, 0, v89
	v_add_f32_e32 v90, 1.0, v90
	v_add_f32_e32 v84, 1.0, v84
	v_rcp_f32_e32 v90, v90
	v_rcp_f32_e32 v84, v84
	v_mul_f32_e32 v88, 0x3fb8aa3b, v88
	v_sqrt_f32_e32 v89, v89
	v_exp_f32_e32 v88, v88
	v_lshlrev_b32_e32 v91, 16, v219
	v_mul_f32_e32 v90, v90, v91
	v_mul_f32_e32 v84, 0xc1000000, v84
	v_mul_f32_e32 v89, v90, v89
	v_mul_f32_e32 v84, v127, v84
	ds_write2st64_b32 v117, v88, v89 offset0:3 offset1:131
	v_mul_f32_e32 v89, -2.0, v84
	v_cmp_ngt_f32_e32 vcc, s76, v89
	s_and_saveexec_b64 s[0:1], vcc
	s_xor_b64 s[0:1], exec, s[0:1]
	v_mul_f32_e32 v88, 0xbfb8aa3b, v89
	v_exp_f32_e32 v88, v88
	s_nop 0
	v_sub_f32_e32 v88, 1.0, v88
	s_andn2_saveexec_b64 s[0:1], s[0:1]
	v_fmamk_f32 v88, v89, 0xbab60b61, v192
	v_fmaak_f32 v88, v89, v88, 0xbd2aaaab
	v_fmaak_f32 v88, v89, v88, 0x3e2aaaab
	v_fma_f32 v88, v89, v88, -0.5
	v_fma_f32 v88, v89, v88, 1.0
	v_mul_f32_e32 v88, v89, v88
	s_or_b64 exec, exec, s[0:1]
	v_add_f32_e32 v80, v125, v80
	v_mul_f32_e32 v80, 0xbfb8aa3b, v80
	v_exp_f32_e32 v80, v80
	v_add_f32_e32 v85, v123, v85
	v_mul_f32_e32 v85, 0xbfb8aa3b, v85
	v_exp_f32_e32 v85, v85
	v_max_f32_e32 v88, v88, v88
	v_add_f32_e32 v80, 1.0, v80
	v_rcp_f32_e32 v80, v80
	v_max_f32_e32 v88, 0, v88
	v_mul_f32_e32 v84, 0x3fb8aa3b, v84
	v_sqrt_f32_e32 v88, v88
	v_add_f32_e32 v85, 1.0, v85
	v_exp_f32_e32 v84, v84
	v_rcp_f32_e32 v85, v85
	v_lshlrev_b32_e32 v89, 16, v218
	v_mul_f32_e32 v80, v80, v89
	v_mul_f32_e32 v80, v80, v88
	ds_write2st64_b32 v117, v84, v80 offset0:16 offset1:144
	v_mul_f32_e32 v80, 0xc1000000, v85
	v_mul_f32_e32 v80, v127, v80
	v_mul_f32_e32 v85, -2.0, v80
	v_cmp_ngt_f32_e32 vcc, s76, v85
	s_and_saveexec_b64 s[0:1], vcc
	s_xor_b64 s[0:1], exec, s[0:1]
	v_mul_f32_e32 v84, 0xbfb8aa3b, v85
	v_exp_f32_e32 v84, v84
	s_nop 0
	v_sub_f32_e32 v84, 1.0, v84
	s_andn2_saveexec_b64 s[0:1], s[0:1]
	v_fmamk_f32 v84, v85, 0xbab60b61, v192
	v_fmaak_f32 v84, v85, v84, 0xbd2aaaab
	v_fmaak_f32 v84, v85, v84, 0x3e2aaaab
	v_fma_f32 v84, v85, v84, -0.5
	v_fma_f32 v84, v85, v84, 1.0
	v_mul_f32_e32 v84, v85, v84
	s_or_b64 exec, exec, s[0:1]
	v_add_f32_e32 v81, v125, v81
	v_mul_f32_e32 v81, 0xbfb8aa3b, v81
	v_exp_f32_e32 v81, v81
	v_add_f32_e32 v85, v123, v86
	v_mul_f32_e32 v85, 0xbfb8aa3b, v85
	v_exp_f32_e32 v85, v85
	v_max_f32_e32 v84, v84, v84
	v_add_f32_e32 v81, 1.0, v81
	v_rcp_f32_e32 v81, v81
	v_max_f32_e32 v84, 0, v84
	v_mul_f32_e32 v80, 0x3fb8aa3b, v80
	v_sqrt_f32_e32 v84, v84
	v_add_f32_e32 v85, 1.0, v85
	v_exp_f32_e32 v80, v80
	v_rcp_f32_e32 v85, v85
	v_lshlrev_b32_e32 v86, 16, v217
	v_mul_f32_e32 v81, v81, v86
	v_mul_f32_e32 v81, v81, v84
	ds_write2st64_b32 v117, v80, v81 offset0:17 offset1:145
	v_mul_f32_e32 v80, 0xc1000000, v85
	v_mul_f32_e32 v80, v127, v80
	v_mul_f32_e32 v84, -2.0, v80
	v_cmp_ngt_f32_e32 vcc, s76, v84
	s_and_saveexec_b64 s[0:1], vcc
	s_xor_b64 s[0:1], exec, s[0:1]
	v_mul_f32_e32 v81, 0xbfb8aa3b, v84
	v_exp_f32_e32 v81, v81
	s_nop 0
	v_sub_f32_e32 v81, 1.0, v81
	s_andn2_saveexec_b64 s[0:1], s[0:1]
	v_fmamk_f32 v81, v84, 0xbab60b61, v192
	v_fmaak_f32 v81, v84, v81, 0xbd2aaaab
	v_fmaak_f32 v81, v84, v81, 0x3e2aaaab
	v_fma_f32 v81, v84, v81, -0.5
	v_fma_f32 v81, v84, v81, 1.0
	v_mul_f32_e32 v81, v84, v81
	s_or_b64 exec, exec, s[0:1]
	v_add_f32_e32 v82, v125, v82
	v_mul_f32_e32 v82, 0xbfb8aa3b, v82
	v_exp_f32_e32 v82, v82
	v_add_f32_e32 v84, v123, v87
	v_mul_f32_e32 v84, 0xbfb8aa3b, v84
	v_exp_f32_e32 v84, v84
	v_max_f32_e32 v81, v81, v81
	v_add_f32_e32 v82, 1.0, v82
	v_rcp_f32_e32 v82, v82
	v_max_f32_e32 v81, 0, v81
	v_mul_f32_e32 v80, 0x3fb8aa3b, v80
	v_sqrt_f32_e32 v81, v81
	v_add_f32_e32 v84, 1.0, v84
	v_exp_f32_e32 v80, v80
	v_rcp_f32_e32 v84, v84
	v_lshlrev_b32_e32 v85, 16, v216
	v_mul_f32_e32 v82, v82, v85
	v_mul_f32_e32 v81, v82, v81
	ds_write2st64_b32 v117, v80, v81 offset0:18 offset1:146
	v_mul_f32_e32 v80, 0xc1000000, v84
	v_mul_f32_e32 v80, v127, v80
	v_mul_f32_e32 v82, -2.0, v80
	v_cmp_ngt_f32_e32 vcc, s76, v82
	s_and_saveexec_b64 s[0:1], vcc
	s_xor_b64 s[0:1], exec, s[0:1]
	v_mul_f32_e32 v81, 0xbfb8aa3b, v82
	v_exp_f32_e32 v81, v81
	s_nop 0
	v_sub_f32_e32 v81, 1.0, v81
	s_andn2_saveexec_b64 s[0:1], s[0:1]
	v_fmamk_f32 v81, v82, 0xbab60b61, v192
	v_fmaak_f32 v81, v82, v81, 0xbd2aaaab
	v_fmaak_f32 v81, v82, v81, 0x3e2aaaab
	v_fma_f32 v81, v82, v81, -0.5
	v_fma_f32 v81, v82, v81, 1.0
	v_mul_f32_e32 v81, v82, v81
	s_or_b64 exec, exec, s[0:1]
	v_add_f32_e32 v82, v125, v83
	v_add_f32_e32 v76, v123, v76
	v_mul_f32_e32 v82, 0xbfb8aa3b, v82
	v_mul_f32_e32 v76, 0xbfb8aa3b, v76
	v_exp_f32_e32 v82, v82
	v_exp_f32_e32 v76, v76
	v_max_f32_e32 v81, v81, v81
	v_max_f32_e32 v81, 0, v81
	v_add_f32_e32 v82, 1.0, v82
	v_add_f32_e32 v76, 1.0, v76
	v_rcp_f32_e32 v82, v82
	v_rcp_f32_e32 v76, v76
	v_mul_f32_e32 v80, 0x3fb8aa3b, v80
	v_sqrt_f32_e32 v81, v81
	v_exp_f32_e32 v80, v80
	v_lshlrev_b32_e32 v83, 16, v215
	v_mul_f32_e32 v82, v82, v83
	v_mul_f32_e32 v76, 0xc1000000, v76
	v_mul_f32_e32 v81, v82, v81
	v_mul_f32_e32 v76, v127, v76
	ds_write2st64_b32 v117, v80, v81 offset0:19 offset1:147
	v_mul_f32_e32 v81, -2.0, v76
	v_cmp_ngt_f32_e32 vcc, s76, v81
	s_and_saveexec_b64 s[0:1], vcc
	s_xor_b64 s[0:1], exec, s[0:1]
	v_mul_f32_e32 v80, 0xbfb8aa3b, v81
	v_exp_f32_e32 v80, v80
	s_nop 0
	v_sub_f32_e32 v80, 1.0, v80
	s_andn2_saveexec_b64 s[0:1], s[0:1]
	v_fmamk_f32 v80, v81, 0xbab60b61, v192
	v_fmaak_f32 v80, v81, v80, 0xbd2aaaab
	v_fmaak_f32 v80, v81, v80, 0x3e2aaaab
	v_fma_f32 v80, v81, v80, -0.5
	v_fma_f32 v80, v81, v80, 1.0
	v_mul_f32_e32 v80, v81, v80
	s_or_b64 exec, exec, s[0:1]
	v_add_f32_e32 v72, v125, v72
	v_mul_f32_e32 v72, 0xbfb8aa3b, v72
	v_exp_f32_e32 v72, v72
	v_add_f32_e32 v77, v123, v77
	v_mul_f32_e32 v77, 0xbfb8aa3b, v77
	v_exp_f32_e32 v77, v77
	v_max_f32_e32 v80, v80, v80
	v_add_f32_e32 v72, 1.0, v72
	v_rcp_f32_e32 v72, v72
	v_max_f32_e32 v80, 0, v80
	v_mul_f32_e32 v76, 0x3fb8aa3b, v76
	v_sqrt_f32_e32 v80, v80
	v_add_f32_e32 v77, 1.0, v77
	v_exp_f32_e32 v76, v76
	v_rcp_f32_e32 v77, v77
	v_lshlrev_b32_e32 v81, 16, v214
	v_mul_f32_e32 v72, v72, v81
	v_mul_f32_e32 v72, v72, v80
	ds_write2st64_b32 v117, v76, v72 offset0:32 offset1:160
	v_mul_f32_e32 v72, 0xc1000000, v77
	v_mul_f32_e32 v72, v127, v72
	v_mul_f32_e32 v77, -2.0, v72
	v_cmp_ngt_f32_e32 vcc, s76, v77
	s_and_saveexec_b64 s[0:1], vcc
	s_xor_b64 s[0:1], exec, s[0:1]
	v_mul_f32_e32 v76, 0xbfb8aa3b, v77
	v_exp_f32_e32 v76, v76
	s_nop 0
	v_sub_f32_e32 v76, 1.0, v76
	s_andn2_saveexec_b64 s[0:1], s[0:1]
	v_fmamk_f32 v76, v77, 0xbab60b61, v192
	v_fmaak_f32 v76, v77, v76, 0xbd2aaaab
	v_fmaak_f32 v76, v77, v76, 0x3e2aaaab
	v_fma_f32 v76, v77, v76, -0.5
	v_fma_f32 v76, v77, v76, 1.0
	v_mul_f32_e32 v76, v77, v76
	s_or_b64 exec, exec, s[0:1]
	v_add_f32_e32 v73, v125, v73
	v_mul_f32_e32 v73, 0xbfb8aa3b, v73
	v_exp_f32_e32 v73, v73
	v_add_f32_e32 v77, v123, v78
	v_mul_f32_e32 v77, 0xbfb8aa3b, v77
	v_exp_f32_e32 v77, v77
	v_max_f32_e32 v76, v76, v76
	v_add_f32_e32 v73, 1.0, v73
	v_rcp_f32_e32 v73, v73
	v_max_f32_e32 v76, 0, v76
	v_mul_f32_e32 v72, 0x3fb8aa3b, v72
	v_sqrt_f32_e32 v76, v76
	v_add_f32_e32 v77, 1.0, v77
	v_exp_f32_e32 v72, v72
	v_rcp_f32_e32 v77, v77
	v_lshlrev_b32_e32 v78, 16, v213
	v_mul_f32_e32 v73, v73, v78
	v_mul_f32_e32 v73, v73, v76
	ds_write2st64_b32 v117, v72, v73 offset0:33 offset1:161
	v_mul_f32_e32 v72, 0xc1000000, v77
	v_mul_f32_e32 v72, v127, v72
	v_mul_f32_e32 v76, -2.0, v72
	v_cmp_ngt_f32_e32 vcc, s76, v76
	s_and_saveexec_b64 s[0:1], vcc
	s_xor_b64 s[0:1], exec, s[0:1]
	v_mul_f32_e32 v73, 0xbfb8aa3b, v76
	v_exp_f32_e32 v73, v73
	s_nop 0
	v_sub_f32_e32 v73, 1.0, v73
	s_andn2_saveexec_b64 s[0:1], s[0:1]
	v_fmamk_f32 v73, v76, 0xbab60b61, v192
	v_fmaak_f32 v73, v76, v73, 0xbd2aaaab
	v_fmaak_f32 v73, v76, v73, 0x3e2aaaab
	v_fma_f32 v73, v76, v73, -0.5
	v_fma_f32 v73, v76, v73, 1.0
	v_mul_f32_e32 v73, v76, v73
	s_or_b64 exec, exec, s[0:1]
	v_add_f32_e32 v74, v125, v74
	v_mul_f32_e32 v74, 0xbfb8aa3b, v74
	v_exp_f32_e32 v74, v74
	v_add_f32_e32 v76, v123, v79
	v_mul_f32_e32 v76, 0xbfb8aa3b, v76
	v_exp_f32_e32 v76, v76
	v_max_f32_e32 v73, v73, v73
	v_add_f32_e32 v74, 1.0, v74
	v_rcp_f32_e32 v74, v74
	v_max_f32_e32 v73, 0, v73
	v_mul_f32_e32 v72, 0x3fb8aa3b, v72
	v_sqrt_f32_e32 v73, v73
	v_add_f32_e32 v76, 1.0, v76
	v_exp_f32_e32 v72, v72
	v_rcp_f32_e32 v76, v76
	v_lshlrev_b32_e32 v77, 16, v212
	v_mul_f32_e32 v74, v74, v77
	v_mul_f32_e32 v73, v74, v73
	ds_write2st64_b32 v117, v72, v73 offset0:34 offset1:162
	v_mul_f32_e32 v72, 0xc1000000, v76
	v_mul_f32_e32 v72, v127, v72
	v_mul_f32_e32 v74, -2.0, v72
	v_cmp_ngt_f32_e32 vcc, s76, v74
	s_and_saveexec_b64 s[0:1], vcc
	s_xor_b64 s[0:1], exec, s[0:1]
	v_mul_f32_e32 v73, 0xbfb8aa3b, v74
	v_exp_f32_e32 v73, v73
	s_nop 0
	v_sub_f32_e32 v73, 1.0, v73
	s_andn2_saveexec_b64 s[0:1], s[0:1]
	v_fmamk_f32 v73, v74, 0xbab60b61, v192
	v_fmaak_f32 v73, v74, v73, 0xbd2aaaab
	v_fmaak_f32 v73, v74, v73, 0x3e2aaaab
	v_fma_f32 v73, v74, v73, -0.5
	v_fma_f32 v73, v74, v73, 1.0
	v_mul_f32_e32 v73, v74, v73
	s_or_b64 exec, exec, s[0:1]
	v_add_f32_e32 v74, v125, v75
	v_add_f32_e32 v60, v123, v60
	v_mul_f32_e32 v74, 0xbfb8aa3b, v74
	v_mul_f32_e32 v60, 0xbfb8aa3b, v60
	v_exp_f32_e32 v74, v74
	v_exp_f32_e32 v60, v60
	v_max_f32_e32 v73, v73, v73
	v_max_f32_e32 v73, 0, v73
	v_add_f32_e32 v74, 1.0, v74
	v_add_f32_e32 v60, 1.0, v60
	v_rcp_f32_e32 v74, v74
	v_rcp_f32_e32 v60, v60
	v_mul_f32_e32 v72, 0x3fb8aa3b, v72
	v_sqrt_f32_e32 v73, v73
	v_exp_f32_e32 v72, v72
	v_lshlrev_b32_e32 v75, 16, v211
	v_mul_f32_e32 v74, v74, v75
	v_mul_f32_e32 v60, 0xc1000000, v60
	v_mul_f32_e32 v73, v74, v73
	v_mul_f32_e32 v60, v127, v60
	ds_write2st64_b32 v117, v72, v73 offset0:35 offset1:163
	v_mul_f32_e32 v73, -2.0, v60
	v_cmp_ngt_f32_e32 vcc, s76, v73
	s_and_saveexec_b64 s[0:1], vcc
	s_xor_b64 s[0:1], exec, s[0:1]
	v_mul_f32_e32 v72, 0xbfb8aa3b, v73
	v_exp_f32_e32 v72, v72
	s_nop 0
	v_sub_f32_e32 v72, 1.0, v72
	s_andn2_saveexec_b64 s[0:1], s[0:1]
	v_fmamk_f32 v72, v73, 0xbab60b61, v192
	v_fmaak_f32 v72, v73, v72, 0xbd2aaaab
	v_fmaak_f32 v72, v73, v72, 0x3e2aaaab
	v_fma_f32 v72, v73, v72, -0.5
	v_fma_f32 v72, v73, v72, 1.0
	v_mul_f32_e32 v72, v73, v72
	s_or_b64 exec, exec, s[0:1]
	v_add_f32_e32 v56, v125, v56
	v_mul_f32_e32 v56, 0xbfb8aa3b, v56
	v_exp_f32_e32 v56, v56
	v_add_f32_e32 v61, v123, v61
	v_mul_f32_e32 v61, 0xbfb8aa3b, v61
	v_exp_f32_e32 v61, v61
	v_max_f32_e32 v72, v72, v72
	v_add_f32_e32 v56, 1.0, v56
	v_rcp_f32_e32 v56, v56
	v_max_f32_e32 v72, 0, v72
	v_mul_f32_e32 v60, 0x3fb8aa3b, v60
	v_sqrt_f32_e32 v72, v72
	v_add_f32_e32 v61, 1.0, v61
	v_exp_f32_e32 v60, v60
	v_rcp_f32_e32 v61, v61
	v_lshlrev_b32_e32 v73, 16, v210
	v_mul_f32_e32 v56, v56, v73
	v_mul_f32_e32 v56, v56, v72
	ds_write2st64_b32 v117, v60, v56 offset0:48 offset1:176
	v_mul_f32_e32 v56, 0xc1000000, v61
	v_mul_f32_e32 v56, v127, v56
	v_mul_f32_e32 v61, -2.0, v56
	v_cmp_ngt_f32_e32 vcc, s76, v61
	s_and_saveexec_b64 s[0:1], vcc
	s_xor_b64 s[0:1], exec, s[0:1]
	v_mul_f32_e32 v60, 0xbfb8aa3b, v61
	v_exp_f32_e32 v60, v60
	s_nop 0
	v_sub_f32_e32 v60, 1.0, v60
	s_andn2_saveexec_b64 s[0:1], s[0:1]
	v_fmamk_f32 v60, v61, 0xbab60b61, v192
	v_fmaak_f32 v60, v61, v60, 0xbd2aaaab
	v_fmaak_f32 v60, v61, v60, 0x3e2aaaab
	v_fma_f32 v60, v61, v60, -0.5
	v_fma_f32 v60, v61, v60, 1.0
	v_mul_f32_e32 v60, v61, v60
	s_or_b64 exec, exec, s[0:1]
	v_add_f32_e32 v57, v125, v57
	v_mul_f32_e32 v57, 0xbfb8aa3b, v57
	v_exp_f32_e32 v57, v57
	v_add_f32_e32 v61, v123, v62
	v_mul_f32_e32 v61, 0xbfb8aa3b, v61
	v_exp_f32_e32 v61, v61
	v_max_f32_e32 v60, v60, v60
	v_add_f32_e32 v57, 1.0, v57
	v_rcp_f32_e32 v57, v57
	v_max_f32_e32 v60, 0, v60
	v_mul_f32_e32 v56, 0x3fb8aa3b, v56
	v_sqrt_f32_e32 v60, v60
	v_add_f32_e32 v61, 1.0, v61
	v_exp_f32_e32 v56, v56
	v_rcp_f32_e32 v61, v61
	v_lshlrev_b32_e32 v62, 16, v209
	v_mul_f32_e32 v57, v57, v62
	v_mul_f32_e32 v57, v57, v60
	ds_write2st64_b32 v117, v56, v57 offset0:49 offset1:177
	v_mul_f32_e32 v56, 0xc1000000, v61
	v_mul_f32_e32 v56, v127, v56
	v_mul_f32_e32 v60, -2.0, v56
	v_cmp_ngt_f32_e32 vcc, s76, v60
	s_and_saveexec_b64 s[0:1], vcc
	s_xor_b64 s[0:1], exec, s[0:1]
	v_mul_f32_e32 v57, 0xbfb8aa3b, v60
	v_exp_f32_e32 v57, v57
	s_nop 0
	v_sub_f32_e32 v57, 1.0, v57
	s_andn2_saveexec_b64 s[0:1], s[0:1]
	v_fmamk_f32 v57, v60, 0xbab60b61, v192
	v_fmaak_f32 v57, v60, v57, 0xbd2aaaab
	v_fmaak_f32 v57, v60, v57, 0x3e2aaaab
	v_fma_f32 v57, v60, v57, -0.5
	v_fma_f32 v57, v60, v57, 1.0
	v_mul_f32_e32 v57, v60, v57
	s_or_b64 exec, exec, s[0:1]
	v_add_f32_e32 v58, v125, v58
	v_mul_f32_e32 v58, 0xbfb8aa3b, v58
	v_exp_f32_e32 v58, v58
	v_add_f32_e32 v60, v123, v63
	v_mul_f32_e32 v60, 0xbfb8aa3b, v60
	v_exp_f32_e32 v60, v60
	v_max_f32_e32 v57, v57, v57
	v_add_f32_e32 v58, 1.0, v58
	v_rcp_f32_e32 v58, v58
	v_max_f32_e32 v57, 0, v57
	v_mul_f32_e32 v56, 0x3fb8aa3b, v56
	v_sqrt_f32_e32 v57, v57
	v_add_f32_e32 v60, 1.0, v60
	v_exp_f32_e32 v56, v56
	v_rcp_f32_e32 v60, v60
	v_lshlrev_b32_e32 v61, 16, v208
	v_mul_f32_e32 v58, v58, v61
	v_mul_f32_e32 v57, v58, v57
	ds_write2st64_b32 v117, v56, v57 offset0:50 offset1:178
	v_mul_f32_e32 v56, 0xc1000000, v60
	v_mul_f32_e32 v56, v127, v56
	v_mul_f32_e32 v58, -2.0, v56
	v_cmp_ngt_f32_e32 vcc, s76, v58
	s_and_saveexec_b64 s[0:1], vcc
	s_xor_b64 s[0:1], exec, s[0:1]
	v_mul_f32_e32 v57, 0xbfb8aa3b, v58
	v_exp_f32_e32 v57, v57
	s_nop 0
	v_sub_f32_e32 v57, 1.0, v57
	s_andn2_saveexec_b64 s[0:1], s[0:1]
	v_fmamk_f32 v57, v58, 0xbab60b61, v192
	v_fmaak_f32 v57, v58, v57, 0xbd2aaaab
	v_fmaak_f32 v57, v58, v57, 0x3e2aaaab
	v_fma_f32 v57, v58, v57, -0.5
	v_fma_f32 v57, v58, v57, 1.0
	v_mul_f32_e32 v57, v58, v57
	s_or_b64 exec, exec, s[0:1]
	v_add_f32_e32 v58, v125, v59
	v_mul_f32_e32 v58, 0xbfb8aa3b, v58
	v_exp_f32_e32 v58, v58
	v_add_f32_e32 v59, v129, v68
	v_mul_f32_e32 v59, 0xbfb8aa3b, v59
	v_exp_f32_e32 v59, v59
	v_max_f32_e32 v57, v57, v57
	v_add_f32_e32 v58, 1.0, v58
	v_rcp_f32_e32 v58, v58
	v_max_f32_e32 v57, 0, v57
	v_mul_f32_e32 v56, 0x3fb8aa3b, v56
	v_sqrt_f32_e32 v57, v57
	v_add_f32_e32 v59, 1.0, v59
	v_exp_f32_e32 v56, v56
	v_rcp_f32_e32 v59, v59
	v_lshlrev_b32_e32 v60, 16, v207
	v_mul_f32_e32 v58, v58, v60
	v_mul_f32_e32 v57, v58, v57
	ds_write2st64_b32 v117, v56, v57 offset0:51 offset1:179
	v_mul_f32_e32 v56, 0xc1000000, v59
	v_mul_f32_e32 v56, v151, v56
	v_mul_f32_e32 v58, -2.0, v56
	v_cmp_ngt_f32_e32 vcc, s76, v58
	s_and_saveexec_b64 s[0:1], vcc
	s_xor_b64 s[0:1], exec, s[0:1]
	v_mul_f32_e32 v57, 0xbfb8aa3b, v58
	v_exp_f32_e32 v57, v57
	s_nop 0
	v_sub_f32_e32 v57, 1.0, v57
	s_andn2_saveexec_b64 s[0:1], s[0:1]
	v_fmamk_f32 v57, v58, 0xbab60b61, v192
	v_fmaak_f32 v57, v58, v57, 0xbd2aaaab
	v_fmaak_f32 v57, v58, v57, 0x3e2aaaab
	v_fma_f32 v57, v58, v57, -0.5
	v_fma_f32 v57, v58, v57, 1.0
	v_mul_f32_e32 v57, v58, v57
	s_or_b64 exec, exec, s[0:1]
	v_add_f32_e32 v58, v131, v64
	v_mul_f32_e32 v58, 0xbfb8aa3b, v58
	v_exp_f32_e32 v58, v58
	v_add_f32_e32 v59, v129, v69
	v_mul_f32_e32 v59, 0xbfb8aa3b, v59
	v_exp_f32_e32 v59, v59
	v_max_f32_e32 v57, v57, v57
	v_add_f32_e32 v58, 1.0, v58
	v_rcp_f32_e32 v58, v58
	v_max_f32_e32 v57, 0, v57
	v_mul_f32_e32 v56, 0x3fb8aa3b, v56
	v_sqrt_f32_e32 v57, v57
	v_add_f32_e32 v59, 1.0, v59
	v_exp_f32_e32 v56, v56
	v_rcp_f32_e32 v59, v59
	v_lshlrev_b32_e32 v60, 16, v206
	v_mul_f32_e32 v58, v58, v60
	v_mul_f32_e32 v57, v58, v57
	ds_write2st64_b32 v117, v56, v57 offset0:64 offset1:192
	v_mul_f32_e32 v56, 0xc1000000, v59
	v_mul_f32_e32 v56, v151, v56
	v_mul_f32_e32 v58, -2.0, v56
	v_cmp_ngt_f32_e32 vcc, s76, v58
	s_and_saveexec_b64 s[0:1], vcc
	s_xor_b64 s[0:1], exec, s[0:1]
	v_mul_f32_e32 v57, 0xbfb8aa3b, v58
	v_exp_f32_e32 v57, v57
	s_nop 0
	v_sub_f32_e32 v57, 1.0, v57
	s_andn2_saveexec_b64 s[0:1], s[0:1]
	v_fmamk_f32 v57, v58, 0xbab60b61, v192
	v_fmaak_f32 v57, v58, v57, 0xbd2aaaab
	v_fmaak_f32 v57, v58, v57, 0x3e2aaaab
	v_fma_f32 v57, v58, v57, -0.5
	v_fma_f32 v57, v58, v57, 1.0
	v_mul_f32_e32 v57, v58, v57
	s_or_b64 exec, exec, s[0:1]
	v_add_f32_e32 v58, v131, v65
	v_mul_f32_e32 v58, 0xbfb8aa3b, v58
	v_exp_f32_e32 v58, v58
	v_add_f32_e32 v59, v129, v70
	v_mul_f32_e32 v59, 0xbfb8aa3b, v59
	v_exp_f32_e32 v59, v59
	v_max_f32_e32 v57, v57, v57
	v_add_f32_e32 v58, 1.0, v58
	v_rcp_f32_e32 v58, v58
	v_max_f32_e32 v57, 0, v57
	v_mul_f32_e32 v56, 0x3fb8aa3b, v56
	v_sqrt_f32_e32 v57, v57
	v_add_f32_e32 v59, 1.0, v59
	v_exp_f32_e32 v56, v56
	v_rcp_f32_e32 v59, v59
	v_lshlrev_b32_e32 v60, 16, v205
	v_mul_f32_e32 v58, v58, v60
	v_mul_f32_e32 v57, v58, v57
	ds_write2st64_b32 v117, v56, v57 offset0:65 offset1:193
	v_mul_f32_e32 v56, 0xc1000000, v59
	v_mul_f32_e32 v56, v151, v56
	v_mul_f32_e32 v58, -2.0, v56
	v_cmp_ngt_f32_e32 vcc, s76, v58
	s_and_saveexec_b64 s[0:1], vcc
	s_xor_b64 s[0:1], exec, s[0:1]
	v_mul_f32_e32 v57, 0xbfb8aa3b, v58
	v_exp_f32_e32 v57, v57
	s_nop 0
	v_sub_f32_e32 v57, 1.0, v57
	s_andn2_saveexec_b64 s[0:1], s[0:1]
	v_fmamk_f32 v57, v58, 0xbab60b61, v192
	v_fmaak_f32 v57, v58, v57, 0xbd2aaaab
	v_fmaak_f32 v57, v58, v57, 0x3e2aaaab
	v_fma_f32 v57, v58, v57, -0.5
	v_fma_f32 v57, v58, v57, 1.0
	v_mul_f32_e32 v57, v58, v57
	s_or_b64 exec, exec, s[0:1]
	v_add_f32_e32 v58, v131, v66
	v_mul_f32_e32 v58, 0xbfb8aa3b, v58
	v_exp_f32_e32 v58, v58
	v_add_f32_e32 v59, v129, v71
	v_mul_f32_e32 v59, 0xbfb8aa3b, v59
	v_exp_f32_e32 v59, v59
	v_max_f32_e32 v57, v57, v57
	v_add_f32_e32 v58, 1.0, v58
	v_rcp_f32_e32 v58, v58
	v_max_f32_e32 v57, 0, v57
	v_mul_f32_e32 v56, 0x3fb8aa3b, v56
	v_sqrt_f32_e32 v57, v57
	v_add_f32_e32 v59, 1.0, v59
	v_exp_f32_e32 v56, v56
	v_rcp_f32_e32 v59, v59
	v_lshlrev_b32_e32 v60, 16, v204
	v_mul_f32_e32 v58, v58, v60
	v_mul_f32_e32 v57, v58, v57
	ds_write2st64_b32 v117, v56, v57 offset0:66 offset1:194
	v_mul_f32_e32 v56, 0xc1000000, v59
	v_mul_f32_e32 v56, v151, v56
	v_mul_f32_e32 v58, -2.0, v56
	v_cmp_ngt_f32_e32 vcc, s76, v58
	s_and_saveexec_b64 s[0:1], vcc
	s_xor_b64 s[0:1], exec, s[0:1]
	v_mul_f32_e32 v57, 0xbfb8aa3b, v58
	v_exp_f32_e32 v57, v57
	s_nop 0
	v_sub_f32_e32 v57, 1.0, v57
	s_andn2_saveexec_b64 s[0:1], s[0:1]
	v_fmamk_f32 v57, v58, 0xbab60b61, v192
	v_fmaak_f32 v57, v58, v57, 0xbd2aaaab
	v_fmaak_f32 v57, v58, v57, 0x3e2aaaab
	v_fma_f32 v57, v58, v57, -0.5
	v_fma_f32 v57, v58, v57, 1.0
	v_mul_f32_e32 v57, v58, v57
	s_or_b64 exec, exec, s[0:1]
	v_add_f32_e32 v58, v131, v67
	v_add_f32_e32 v52, v129, v52
	v_mul_f32_e32 v58, 0xbfb8aa3b, v58
	v_mul_f32_e32 v52, 0xbfb8aa3b, v52
	v_exp_f32_e32 v58, v58
	v_exp_f32_e32 v52, v52
	v_max_f32_e32 v57, v57, v57
	v_max_f32_e32 v57, 0, v57
	v_add_f32_e32 v58, 1.0, v58
	v_add_f32_e32 v52, 1.0, v52
	v_rcp_f32_e32 v58, v58
	v_rcp_f32_e32 v52, v52
	v_mul_f32_e32 v56, 0x3fb8aa3b, v56
	v_sqrt_f32_e32 v57, v57
	v_exp_f32_e32 v56, v56
	v_lshlrev_b32_e32 v59, 16, v203
	v_mul_f32_e32 v58, v58, v59
	v_mul_f32_e32 v52, 0xc1000000, v52
	v_mul_f32_e32 v57, v58, v57
	v_mul_f32_e32 v52, v151, v52
	ds_write2st64_b32 v117, v56, v57 offset0:67 offset1:195
	v_mul_f32_e32 v57, -2.0, v52
	v_cmp_ngt_f32_e32 vcc, s76, v57
	s_and_saveexec_b64 s[0:1], vcc
	s_xor_b64 s[0:1], exec, s[0:1]
	v_mul_f32_e32 v56, 0xbfb8aa3b, v57
	v_exp_f32_e32 v56, v56
	s_nop 0
	v_sub_f32_e32 v56, 1.0, v56
	s_andn2_saveexec_b64 s[0:1], s[0:1]
	v_fmamk_f32 v56, v57, 0xbab60b61, v192
	v_fmaak_f32 v56, v57, v56, 0xbd2aaaab
	v_fmaak_f32 v56, v57, v56, 0x3e2aaaab
	v_fma_f32 v56, v57, v56, -0.5
	v_fma_f32 v56, v57, v56, 1.0
	v_mul_f32_e32 v56, v57, v56
	s_or_b64 exec, exec, s[0:1]
	v_add_f32_e32 v48, v131, v48
	v_mul_f32_e32 v48, 0xbfb8aa3b, v48
	v_exp_f32_e32 v48, v48
	v_add_f32_e32 v53, v129, v53
	v_mul_f32_e32 v53, 0xbfb8aa3b, v53
	v_exp_f32_e32 v53, v53
	v_max_f32_e32 v56, v56, v56
	v_add_f32_e32 v48, 1.0, v48
	v_rcp_f32_e32 v48, v48
	v_max_f32_e32 v56, 0, v56
	v_mul_f32_e32 v52, 0x3fb8aa3b, v52
	v_sqrt_f32_e32 v56, v56
	v_add_f32_e32 v53, 1.0, v53
	v_exp_f32_e32 v52, v52
	v_rcp_f32_e32 v53, v53
	v_lshlrev_b32_e32 v57, 16, v202
	v_mul_f32_e32 v48, v48, v57
	v_mul_f32_e32 v48, v48, v56
	ds_write2st64_b32 v117, v52, v48 offset0:80 offset1:208
	v_mul_f32_e32 v48, 0xc1000000, v53
	v_mul_f32_e32 v48, v151, v48
	v_mul_f32_e32 v53, -2.0, v48
	v_cmp_ngt_f32_e32 vcc, s76, v53
	s_and_saveexec_b64 s[0:1], vcc
	s_xor_b64 s[0:1], exec, s[0:1]
	v_mul_f32_e32 v52, 0xbfb8aa3b, v53
	v_exp_f32_e32 v52, v52
	s_nop 0
	v_sub_f32_e32 v52, 1.0, v52
	s_andn2_saveexec_b64 s[0:1], s[0:1]
	v_fmamk_f32 v52, v53, 0xbab60b61, v192
	v_fmaak_f32 v52, v53, v52, 0xbd2aaaab
	v_fmaak_f32 v52, v53, v52, 0x3e2aaaab
	v_fma_f32 v52, v53, v52, -0.5
	v_fma_f32 v52, v53, v52, 1.0
	v_mul_f32_e32 v52, v53, v52
	s_or_b64 exec, exec, s[0:1]
	v_add_f32_e32 v49, v131, v49
	v_mul_f32_e32 v49, 0xbfb8aa3b, v49
	v_exp_f32_e32 v49, v49
	v_add_f32_e32 v53, v129, v54
	v_mul_f32_e32 v53, 0xbfb8aa3b, v53
	v_exp_f32_e32 v53, v53
	v_max_f32_e32 v52, v52, v52
	v_add_f32_e32 v49, 1.0, v49
	v_rcp_f32_e32 v49, v49
	v_max_f32_e32 v52, 0, v52
	v_mul_f32_e32 v48, 0x3fb8aa3b, v48
	v_sqrt_f32_e32 v52, v52
	v_add_f32_e32 v53, 1.0, v53
	v_exp_f32_e32 v48, v48
	v_rcp_f32_e32 v53, v53
	v_lshlrev_b32_e32 v54, 16, v201
	v_mul_f32_e32 v49, v49, v54
	v_mul_f32_e32 v49, v49, v52
	ds_write2st64_b32 v117, v48, v49 offset0:81 offset1:209
	v_mul_f32_e32 v48, 0xc1000000, v53
	v_mul_f32_e32 v48, v151, v48
	v_mul_f32_e32 v52, -2.0, v48
	v_cmp_ngt_f32_e32 vcc, s76, v52
	s_and_saveexec_b64 s[0:1], vcc
	s_xor_b64 s[0:1], exec, s[0:1]
	v_mul_f32_e32 v49, 0xbfb8aa3b, v52
	v_exp_f32_e32 v49, v49
	s_nop 0
	v_sub_f32_e32 v49, 1.0, v49
	s_andn2_saveexec_b64 s[0:1], s[0:1]
	v_fmamk_f32 v49, v52, 0xbab60b61, v192
	v_fmaak_f32 v49, v52, v49, 0xbd2aaaab
	v_fmaak_f32 v49, v52, v49, 0x3e2aaaab
	v_fma_f32 v49, v52, v49, -0.5
	v_fma_f32 v49, v52, v49, 1.0
	v_mul_f32_e32 v49, v52, v49
	s_or_b64 exec, exec, s[0:1]
	v_add_f32_e32 v50, v131, v50
	v_mul_f32_e32 v50, 0xbfb8aa3b, v50
	v_exp_f32_e32 v50, v50
	v_add_f32_e32 v52, v129, v55
	v_mul_f32_e32 v52, 0xbfb8aa3b, v52
	v_exp_f32_e32 v52, v52
	v_max_f32_e32 v49, v49, v49
	v_add_f32_e32 v50, 1.0, v50
	v_rcp_f32_e32 v50, v50
	v_max_f32_e32 v49, 0, v49
	v_mul_f32_e32 v48, 0x3fb8aa3b, v48
	v_sqrt_f32_e32 v49, v49
	v_add_f32_e32 v52, 1.0, v52
	v_exp_f32_e32 v48, v48
	v_rcp_f32_e32 v52, v52
	v_lshlrev_b32_e32 v53, 16, v200
	v_mul_f32_e32 v50, v50, v53
	v_mul_f32_e32 v49, v50, v49
	ds_write2st64_b32 v117, v48, v49 offset0:82 offset1:210
	v_mul_f32_e32 v48, 0xc1000000, v52
	v_mul_f32_e32 v48, v151, v48
	v_mul_f32_e32 v50, -2.0, v48
	v_cmp_ngt_f32_e32 vcc, s76, v50
	s_and_saveexec_b64 s[0:1], vcc
	s_xor_b64 s[0:1], exec, s[0:1]
	v_mul_f32_e32 v49, 0xbfb8aa3b, v50
	v_exp_f32_e32 v49, v49
	s_nop 0
	v_sub_f32_e32 v49, 1.0, v49
	s_andn2_saveexec_b64 s[0:1], s[0:1]
	v_fmamk_f32 v49, v50, 0xbab60b61, v192
	v_fmaak_f32 v49, v50, v49, 0xbd2aaaab
	v_fmaak_f32 v49, v50, v49, 0x3e2aaaab
	v_fma_f32 v49, v50, v49, -0.5
	v_fma_f32 v49, v50, v49, 1.0
	v_mul_f32_e32 v49, v50, v49
	s_or_b64 exec, exec, s[0:1]
	v_add_f32_e32 v50, v131, v51
	v_add_f32_e32 v44, v129, v44
	v_mul_f32_e32 v50, 0xbfb8aa3b, v50
	v_mul_f32_e32 v44, 0xbfb8aa3b, v44
	v_exp_f32_e32 v50, v50
	v_exp_f32_e32 v44, v44
	v_max_f32_e32 v49, v49, v49
	v_max_f32_e32 v49, 0, v49
	v_add_f32_e32 v50, 1.0, v50
	v_add_f32_e32 v44, 1.0, v44
	v_rcp_f32_e32 v50, v50
	v_rcp_f32_e32 v44, v44
	v_mul_f32_e32 v48, 0x3fb8aa3b, v48
	v_sqrt_f32_e32 v49, v49
	v_exp_f32_e32 v48, v48
	v_lshlrev_b32_e32 v51, 16, v199
	v_mul_f32_e32 v50, v50, v51
	v_mul_f32_e32 v44, 0xc1000000, v44
	v_mul_f32_e32 v49, v50, v49
	v_mul_f32_e32 v44, v151, v44
	ds_write2st64_b32 v117, v48, v49 offset0:83 offset1:211
	v_mul_f32_e32 v49, -2.0, v44
	v_cmp_ngt_f32_e32 vcc, s76, v49
	s_and_saveexec_b64 s[0:1], vcc
	s_xor_b64 s[0:1], exec, s[0:1]
	v_mul_f32_e32 v48, 0xbfb8aa3b, v49
	v_exp_f32_e32 v48, v48
	s_nop 0
	v_sub_f32_e32 v48, 1.0, v48
	s_andn2_saveexec_b64 s[0:1], s[0:1]
	v_fmamk_f32 v48, v49, 0xbab60b61, v192
	v_fmaak_f32 v48, v49, v48, 0xbd2aaaab
	v_fmaak_f32 v48, v49, v48, 0x3e2aaaab
	v_fma_f32 v48, v49, v48, -0.5
	v_fma_f32 v48, v49, v48, 1.0
	v_mul_f32_e32 v48, v49, v48
	s_or_b64 exec, exec, s[0:1]
	v_add_f32_e32 v40, v131, v40
	v_mul_f32_e32 v40, 0xbfb8aa3b, v40
	v_exp_f32_e32 v40, v40
	v_add_f32_e32 v45, v129, v45
	v_mul_f32_e32 v45, 0xbfb8aa3b, v45
	v_exp_f32_e32 v45, v45
	v_max_f32_e32 v48, v48, v48
	v_add_f32_e32 v40, 1.0, v40
	v_rcp_f32_e32 v40, v40
	v_max_f32_e32 v48, 0, v48
	v_mul_f32_e32 v44, 0x3fb8aa3b, v44
	v_sqrt_f32_e32 v48, v48
	v_add_f32_e32 v45, 1.0, v45
	v_exp_f32_e32 v44, v44
	v_rcp_f32_e32 v45, v45
	v_lshlrev_b32_e32 v49, 16, v187
	v_mul_f32_e32 v40, v40, v49
	v_mul_f32_e32 v40, v40, v48
	ds_write2st64_b32 v117, v44, v40 offset0:96 offset1:224
	v_mul_f32_e32 v40, 0xc1000000, v45
	v_mul_f32_e32 v40, v151, v40
	v_mul_f32_e32 v45, -2.0, v40
	v_cmp_ngt_f32_e32 vcc, s76, v45
	s_and_saveexec_b64 s[0:1], vcc
	s_xor_b64 s[0:1], exec, s[0:1]
	v_mul_f32_e32 v44, 0xbfb8aa3b, v45
	v_exp_f32_e32 v44, v44
	s_nop 0
	v_sub_f32_e32 v44, 1.0, v44
	s_andn2_saveexec_b64 s[0:1], s[0:1]
	v_fmamk_f32 v44, v45, 0xbab60b61, v192
	v_fmaak_f32 v44, v45, v44, 0xbd2aaaab
	v_fmaak_f32 v44, v45, v44, 0x3e2aaaab
	v_fma_f32 v44, v45, v44, -0.5
	v_fma_f32 v44, v45, v44, 1.0
	v_mul_f32_e32 v44, v45, v44
	s_or_b64 exec, exec, s[0:1]
	v_add_f32_e32 v41, v131, v41
	v_mul_f32_e32 v41, 0xbfb8aa3b, v41
	v_exp_f32_e32 v41, v41
	v_add_f32_e32 v45, v129, v46
	v_mul_f32_e32 v45, 0xbfb8aa3b, v45
	v_exp_f32_e32 v45, v45
	v_max_f32_e32 v44, v44, v44
	v_add_f32_e32 v41, 1.0, v41
	v_rcp_f32_e32 v41, v41
	v_max_f32_e32 v44, 0, v44
	v_mul_f32_e32 v40, 0x3fb8aa3b, v40
	v_sqrt_f32_e32 v44, v44
	v_add_f32_e32 v45, 1.0, v45
	v_exp_f32_e32 v40, v40
	v_rcp_f32_e32 v45, v45
	v_lshlrev_b32_e32 v46, 16, v186
	v_mul_f32_e32 v41, v41, v46
	v_mul_f32_e32 v41, v41, v44
	ds_write2st64_b32 v117, v40, v41 offset0:97 offset1:225
	v_mul_f32_e32 v40, 0xc1000000, v45
	v_mul_f32_e32 v40, v151, v40
	v_mul_f32_e32 v44, -2.0, v40
	v_cmp_ngt_f32_e32 vcc, s76, v44
	s_and_saveexec_b64 s[0:1], vcc
	s_xor_b64 s[0:1], exec, s[0:1]
	v_mul_f32_e32 v41, 0xbfb8aa3b, v44
	v_exp_f32_e32 v41, v41
	s_nop 0
	v_sub_f32_e32 v41, 1.0, v41
	s_andn2_saveexec_b64 s[0:1], s[0:1]
	v_fmamk_f32 v41, v44, 0xbab60b61, v192
	v_fmaak_f32 v41, v44, v41, 0xbd2aaaab
	v_fmaak_f32 v41, v44, v41, 0x3e2aaaab
	v_fma_f32 v41, v44, v41, -0.5
	v_fma_f32 v41, v44, v41, 1.0
	v_mul_f32_e32 v41, v44, v41
	s_or_b64 exec, exec, s[0:1]
	v_add_f32_e32 v42, v131, v42
	v_mul_f32_e32 v42, 0xbfb8aa3b, v42
	v_exp_f32_e32 v42, v42
	v_add_f32_e32 v44, v129, v47
	v_mul_f32_e32 v44, 0xbfb8aa3b, v44
	v_exp_f32_e32 v44, v44
	v_max_f32_e32 v41, v41, v41
	v_add_f32_e32 v42, 1.0, v42
	v_rcp_f32_e32 v42, v42
	v_max_f32_e32 v41, 0, v41
	v_mul_f32_e32 v40, 0x3fb8aa3b, v40
	v_sqrt_f32_e32 v41, v41
	v_add_f32_e32 v44, 1.0, v44
	v_exp_f32_e32 v40, v40
	v_rcp_f32_e32 v44, v44
	v_lshlrev_b32_e32 v45, 16, v185
	v_mul_f32_e32 v42, v42, v45
	v_mul_f32_e32 v41, v42, v41
	ds_write2st64_b32 v117, v40, v41 offset0:98 offset1:226
	v_mul_f32_e32 v40, 0xc1000000, v44
	v_mul_f32_e32 v40, v151, v40
	v_mul_f32_e32 v42, -2.0, v40
	v_cmp_ngt_f32_e32 vcc, s76, v42
	s_and_saveexec_b64 s[0:1], vcc
	s_xor_b64 s[0:1], exec, s[0:1]
	v_mul_f32_e32 v41, 0xbfb8aa3b, v42
	v_exp_f32_e32 v41, v41
	s_nop 0
	v_sub_f32_e32 v41, 1.0, v41
	s_andn2_saveexec_b64 s[0:1], s[0:1]
	v_fmamk_f32 v41, v42, 0xbab60b61, v192
	v_fmaak_f32 v41, v42, v41, 0xbd2aaaab
	v_fmaak_f32 v41, v42, v41, 0x3e2aaaab
	v_fma_f32 v41, v42, v41, -0.5
	v_fma_f32 v41, v42, v41, 1.0
	v_mul_f32_e32 v41, v42, v41
	s_or_b64 exec, exec, s[0:1]
	v_add_f32_e32 v42, v131, v43
	v_add_f32_e32 v36, v129, v36
	v_mul_f32_e32 v42, 0xbfb8aa3b, v42
	v_mul_f32_e32 v36, 0xbfb8aa3b, v36
	v_exp_f32_e32 v42, v42
	v_exp_f32_e32 v36, v36
	v_max_f32_e32 v41, v41, v41
	v_max_f32_e32 v41, 0, v41
	v_add_f32_e32 v42, 1.0, v42
	v_add_f32_e32 v36, 1.0, v36
	v_rcp_f32_e32 v42, v42
	v_rcp_f32_e32 v36, v36
	v_mul_f32_e32 v40, 0x3fb8aa3b, v40
	v_sqrt_f32_e32 v41, v41
	v_exp_f32_e32 v40, v40
	v_lshlrev_b32_e32 v43, 16, v184
	v_mul_f32_e32 v42, v42, v43
	v_mul_f32_e32 v36, 0xc1000000, v36
	v_mul_f32_e32 v41, v42, v41
	v_mul_f32_e32 v36, v151, v36
	ds_write2st64_b32 v117, v40, v41 offset0:99 offset1:227
	v_mul_f32_e32 v41, -2.0, v36
	v_cmp_ngt_f32_e32 vcc, s76, v41
	s_and_saveexec_b64 s[0:1], vcc
	s_xor_b64 s[0:1], exec, s[0:1]
	v_mul_f32_e32 v40, 0xbfb8aa3b, v41
	v_exp_f32_e32 v40, v40
	s_nop 0
	v_sub_f32_e32 v40, 1.0, v40
	s_andn2_saveexec_b64 s[0:1], s[0:1]
	v_fmamk_f32 v40, v41, 0xbab60b61, v192
	v_fmaak_f32 v40, v41, v40, 0xbd2aaaab
	v_fmaak_f32 v40, v41, v40, 0x3e2aaaab
	v_fma_f32 v40, v41, v40, -0.5
	v_fma_f32 v40, v41, v40, 1.0
	v_mul_f32_e32 v40, v41, v40
	s_or_b64 exec, exec, s[0:1]
	v_add_f32_e32 v32, v131, v32
	v_mul_f32_e32 v32, 0xbfb8aa3b, v32
	v_exp_f32_e32 v32, v32
	v_add_f32_e32 v37, v129, v37
	v_mul_f32_e32 v37, 0xbfb8aa3b, v37
	v_exp_f32_e32 v37, v37
	v_max_f32_e32 v40, v40, v40
	v_add_f32_e32 v32, 1.0, v32
	v_rcp_f32_e32 v32, v32
	v_max_f32_e32 v40, 0, v40
	v_mul_f32_e32 v36, 0x3fb8aa3b, v36
	v_sqrt_f32_e32 v40, v40
	v_add_f32_e32 v37, 1.0, v37
	v_exp_f32_e32 v36, v36
	v_rcp_f32_e32 v37, v37
	v_lshlrev_b32_e32 v41, 16, v183
	v_mul_f32_e32 v32, v32, v41
	v_mul_f32_e32 v32, v32, v40
	ds_write2st64_b32 v117, v36, v32 offset0:112 offset1:240
	v_mul_f32_e32 v32, 0xc1000000, v37
	v_mul_f32_e32 v32, v151, v32
	v_mul_f32_e32 v37, -2.0, v32
	v_cmp_ngt_f32_e32 vcc, s76, v37
	s_and_saveexec_b64 s[0:1], vcc
	s_xor_b64 s[0:1], exec, s[0:1]
	v_mul_f32_e32 v36, 0xbfb8aa3b, v37
	v_exp_f32_e32 v36, v36
	s_nop 0
	v_sub_f32_e32 v36, 1.0, v36
	s_andn2_saveexec_b64 s[0:1], s[0:1]
	v_fmamk_f32 v36, v37, 0xbab60b61, v192
	v_fmaak_f32 v36, v37, v36, 0xbd2aaaab
	v_fmaak_f32 v36, v37, v36, 0x3e2aaaab
	v_fma_f32 v36, v37, v36, -0.5
	v_fma_f32 v36, v37, v36, 1.0
	v_mul_f32_e32 v36, v37, v36
	s_or_b64 exec, exec, s[0:1]
	v_add_f32_e32 v33, v131, v33
	v_mul_f32_e32 v33, 0xbfb8aa3b, v33
	v_exp_f32_e32 v33, v33
	v_add_f32_e32 v37, v129, v38
	v_mul_f32_e32 v37, 0xbfb8aa3b, v37
	v_exp_f32_e32 v37, v37
	v_max_f32_e32 v36, v36, v36
	v_add_f32_e32 v33, 1.0, v33
	v_rcp_f32_e32 v33, v33
	v_max_f32_e32 v36, 0, v36
	v_mul_f32_e32 v32, 0x3fb8aa3b, v32
	v_sqrt_f32_e32 v36, v36
	v_add_f32_e32 v37, 1.0, v37
	v_exp_f32_e32 v32, v32
	v_rcp_f32_e32 v37, v37
	v_lshlrev_b32_e32 v38, 16, v182
	v_mul_f32_e32 v33, v33, v38
	v_mul_f32_e32 v33, v33, v36
	ds_write2st64_b32 v117, v32, v33 offset0:113 offset1:241
	v_mul_f32_e32 v32, 0xc1000000, v37
	v_mul_f32_e32 v32, v151, v32
	v_mul_f32_e32 v36, -2.0, v32
	v_cmp_ngt_f32_e32 vcc, s76, v36
	s_and_saveexec_b64 s[0:1], vcc
	s_xor_b64 s[0:1], exec, s[0:1]
	v_mul_f32_e32 v33, 0xbfb8aa3b, v36
	v_exp_f32_e32 v33, v33
	s_nop 0
	v_sub_f32_e32 v33, 1.0, v33
	s_andn2_saveexec_b64 s[0:1], s[0:1]
	v_fmamk_f32 v33, v36, 0xbab60b61, v192
	v_fmaak_f32 v33, v36, v33, 0xbd2aaaab
	v_fmaak_f32 v33, v36, v33, 0x3e2aaaab
	v_fma_f32 v33, v36, v33, -0.5
	v_fma_f32 v33, v36, v33, 1.0
	v_mul_f32_e32 v33, v36, v33
	s_or_b64 exec, exec, s[0:1]
	v_add_f32_e32 v34, v131, v34
	v_mul_f32_e32 v34, 0xbfb8aa3b, v34
	v_exp_f32_e32 v34, v34
	v_add_f32_e32 v36, v129, v39
	v_mul_f32_e32 v36, 0xbfb8aa3b, v36
	v_exp_f32_e32 v36, v36
	v_max_f32_e32 v33, v33, v33
	v_add_f32_e32 v34, 1.0, v34
	v_rcp_f32_e32 v34, v34
	v_max_f32_e32 v33, 0, v33
	v_mul_f32_e32 v32, 0x3fb8aa3b, v32
	v_sqrt_f32_e32 v33, v33
	v_add_f32_e32 v36, 1.0, v36
	v_exp_f32_e32 v32, v32
	v_rcp_f32_e32 v36, v36
	v_lshlrev_b32_e32 v37, 16, v181
	v_mul_f32_e32 v34, v34, v37
	v_mul_f32_e32 v33, v34, v33
	ds_write2st64_b32 v117, v32, v33 offset0:114 offset1:242
	v_mul_f32_e32 v32, 0xc1000000, v36
	v_mul_f32_e32 v32, v151, v32
	v_mul_f32_e32 v34, -2.0, v32
	v_cmp_ngt_f32_e32 vcc, s76, v34
	s_and_saveexec_b64 s[0:1], vcc
	s_xor_b64 s[0:1], exec, s[0:1]
	v_mul_f32_e32 v33, 0xbfb8aa3b, v34
	v_exp_f32_e32 v33, v33
	s_nop 0
	v_sub_f32_e32 v33, 1.0, v33
	s_andn2_saveexec_b64 s[0:1], s[0:1]
	v_fmamk_f32 v33, v34, 0xbab60b61, v192
	v_fmaak_f32 v33, v34, v33, 0xbd2aaaab
	v_fmaak_f32 v33, v34, v33, 0x3e2aaaab
	v_fma_f32 v33, v34, v33, -0.5
	v_fma_f32 v33, v34, v33, 1.0
	v_mul_f32_e32 v33, v34, v33
	s_or_b64 exec, exec, s[0:1]
	v_add_f32_e32 v34, v131, v35
	v_mul_f32_e32 v34, 0xbfb8aa3b, v34
	v_exp_f32_e32 v34, v34
	v_max_f32_e32 v33, v33, v33
	v_max_f32_e32 v33, 0, v33
	v_mul_f32_e32 v32, 0x3fb8aa3b, v32
	v_add_f32_e32 v34, 1.0, v34
	v_rcp_f32_e32 v34, v34
	v_sqrt_f32_e32 v33, v33
	v_exp_f32_e32 v32, v32
	v_lshlrev_b32_e32 v35, 16, v149
	v_mul_f32_e32 v34, v34, v35
	v_mul_f32_e32 v33, v34, v33
	ds_write2st64_b32 v117, v32, v33 offset0:115 offset1:243
	s_waitcnt lgkmcnt(0)
	s_barrier
	s_and_saveexec_b64 s[0:1], s[2:3]
	s_cbranch_execz .LBB0_1073
	s_and_b64 vcc, exec, s[4:5]
	s_cbranch_vccz .Llru_scan_bwd
	ds_read2st64_b32 v[32:33], v179 offset0:0 offset1:128
	ds_read2st64_b32 v[34:35], v179 offset0:1 offset1:129
	ds_read2st64_b32 v[36:37], v179 offset0:2 offset1:130
	ds_read2st64_b32 v[38:39], v179 offset0:3 offset1:131
	ds_read2st64_b32 v[40:41], v179 offset0:4 offset1:132
	ds_read2st64_b32 v[42:43], v179 offset0:5 offset1:133
	ds_read2st64_b32 v[44:45], v179 offset0:6 offset1:134
	s_waitcnt lgkmcnt(6)
	v_fmac_f32_e32 v33, v99, v32
	ds_write_b32 v179, v33 offset:32768
	ds_read2st64_b32 v[46:47], v179 offset0:7 offset1:135
	s_waitcnt lgkmcnt(7)
	v_fmac_f32_e32 v35, v33, v34
	ds_write_b32 v179, v35 offset:33024
	ds_read2st64_b32 v[48:49], v179 offset0:8 offset1:136
	s_waitcnt lgkmcnt(8)
	v_fmac_f32_e32 v37, v35, v36
	ds_write_b32 v179, v37 offset:33280
	ds_read2st64_b32 v[50:51], v179 offset0:9 offset1:137
	s_waitcnt lgkmcnt(9)
	v_fmac_f32_e32 v39, v37, v38
	ds_write_b32 v179, v39 offset:33536
	ds_read2st64_b32 v[52:53], v179 offset0:10 offset1:138
	s_waitcnt lgkmcnt(10)
	v_fmac_f32_e32 v41, v39, v40
	ds_write_b32 v179, v41 offset:33792
	ds_read2st64_b32 v[54:55], v179 offset0:11 offset1:139
	s_waitcnt lgkmcnt(11)
	v_fmac_f32_e32 v43, v41, v42
	ds_write_b32 v179, v43 offset:34048
	ds_read2st64_b32 v[56:57], v179 offset0:12 offset1:140
	s_waitcnt lgkmcnt(12)
	v_fmac_f32_e32 v45, v43, v44
	ds_write_b32 v179, v45 offset:34304
	ds_read2st64_b32 v[58:59], v179 offset0:13 offset1:141
	s_waitcnt lgkmcnt(12)
	v_fmac_f32_e32 v47, v45, v46
	ds_write_b32 v179, v47 offset:34560
	ds_read2st64_b32 v[60:61], v179 offset0:14 offset1:142
	s_waitcnt lgkmcnt(12)
	v_fmac_f32_e32 v49, v47, v48
	ds_write_b32 v179, v49 offset:34816
	ds_read2st64_b32 v[62:63], v179 offset0:15 offset1:143
	s_waitcnt lgkmcnt(12)
	v_fmac_f32_e32 v51, v49, v50
	ds_write_b32 v179, v51 offset:35072
	ds_read2st64_b32 v[32:33], v179 offset0:16 offset1:144
	s_waitcnt lgkmcnt(12)
	v_fmac_f32_e32 v53, v51, v52
	ds_write_b32 v179, v53 offset:35328
	ds_read2st64_b32 v[34:35], v179 offset0:17 offset1:145
	s_waitcnt lgkmcnt(12)
	v_fmac_f32_e32 v55, v53, v54
	ds_write_b32 v179, v55 offset:35584
	ds_read2st64_b32 v[36:37], v179 offset0:18 offset1:146
	s_waitcnt lgkmcnt(12)
	v_fmac_f32_e32 v57, v55, v56
	ds_write_b32 v179, v57 offset:35840
	ds_read2st64_b32 v[38:39], v179 offset0:19 offset1:147
	s_waitcnt lgkmcnt(12)
	v_fmac_f32_e32 v59, v57, v58
	ds_write_b32 v179, v59 offset:36096
	ds_read2st64_b32 v[40:41], v179 offset0:20 offset1:148
	s_waitcnt lgkmcnt(12)
	v_fmac_f32_e32 v61, v59, v60
	ds_write_b32 v179, v61 offset:36352
	ds_read2st64_b32 v[42:43], v179 offset0:21 offset1:149
	s_waitcnt lgkmcnt(12)
	v_fmac_f32_e32 v63, v61, v62
	ds_write_b32 v179, v63 offset:36608
	ds_read2st64_b32 v[44:45], v179 offset0:22 offset1:150
	s_waitcnt lgkmcnt(12)
	v_fmac_f32_e32 v33, v63, v32
	ds_write_b32 v179, v33 offset:36864
	ds_read2st64_b32 v[46:47], v179 offset0:23 offset1:151
	s_waitcnt lgkmcnt(12)
	v_fmac_f32_e32 v35, v33, v34
	ds_write_b32 v179, v35 offset:37120
	ds_read2st64_b32 v[48:49], v179 offset0:24 offset1:152
	s_waitcnt lgkmcnt(12)
	v_fmac_f32_e32 v37, v35, v36
	ds_write_b32 v179, v37 offset:37376
	ds_read2st64_b32 v[50:51], v179 offset0:25 offset1:153
	s_waitcnt lgkmcnt(12)
	v_fmac_f32_e32 v39, v37, v38
	ds_write_b32 v179, v39 offset:37632
	ds_read2st64_b32 v[52:53], v179 offset0:26 offset1:154
	s_waitcnt lgkmcnt(12)
	v_fmac_f32_e32 v41, v39, v40
	ds_write_b32 v179, v41 offset:37888
	ds_read2st64_b32 v[54:55], v179 offset0:27 offset1:155
	s_waitcnt lgkmcnt(12)
	v_fmac_f32_e32 v43, v41, v42
	ds_write_b32 v179, v43 offset:38144
	ds_read2st64_b32 v[56:57], v179 offset0:28 offset1:156
	s_waitcnt lgkmcnt(12)
	v_fmac_f32_e32 v45, v43, v44
	ds_write_b32 v179, v45 offset:38400
	ds_read2st64_b32 v[58:59], v179 offset0:29 offset1:157
	s_waitcnt lgkmcnt(12)
	v_fmac_f32_e32 v47, v45, v46
	ds_write_b32 v179, v47 offset:38656
	ds_read2st64_b32 v[60:61], v179 offset0:30 offset1:158
	s_waitcnt lgkmcnt(12)
	v_fmac_f32_e32 v49, v47, v48
	ds_write_b32 v179, v49 offset:38912
	ds_read2st64_b32 v[62:63], v179 offset0:31 offset1:159
	s_waitcnt lgkmcnt(12)
	v_fmac_f32_e32 v51, v49, v50
	ds_write_b32 v179, v51 offset:39168
	ds_read2st64_b32 v[32:33], v179 offset0:32 offset1:160
	s_waitcnt lgkmcnt(12)
	v_fmac_f32_e32 v53, v51, v52
	ds_write_b32 v179, v53 offset:39424
	ds_read2st64_b32 v[34:35], v179 offset0:33 offset1:161
	s_waitcnt lgkmcnt(12)
	v_fmac_f32_e32 v55, v53, v54
	ds_write_b32 v179, v55 offset:39680
	ds_read2st64_b32 v[36:37], v179 offset0:34 offset1:162
	s_waitcnt lgkmcnt(12)
	v_fmac_f32_e32 v57, v55, v56
	ds_write_b32 v179, v57 offset:39936
	ds_read2st64_b32 v[38:39], v179 offset0:35 offset1:163
	s_waitcnt lgkmcnt(12)
	v_fmac_f32_e32 v59, v57, v58
	ds_write_b32 v179, v59 offset:40192
	ds_read2st64_b32 v[40:41], v179 offset0:36 offset1:164
	s_waitcnt lgkmcnt(12)
	v_fmac_f32_e32 v61, v59, v60
	ds_write_b32 v179, v61 offset:40448
	ds_read2st64_b32 v[42:43], v179 offset0:37 offset1:165
	s_waitcnt lgkmcnt(12)
	v_fmac_f32_e32 v63, v61, v62
	ds_write_b32 v179, v63 offset:40704
	ds_read2st64_b32 v[44:45], v179 offset0:38 offset1:166
	s_waitcnt lgkmcnt(12)
	v_fmac_f32_e32 v33, v63, v32
	ds_write_b32 v179, v33 offset:40960
	ds_read2st64_b32 v[46:47], v179 offset0:39 offset1:167
	s_waitcnt lgkmcnt(12)
	v_fmac_f32_e32 v35, v33, v34
	ds_write_b32 v179, v35 offset:41216
	ds_read2st64_b32 v[48:49], v179 offset0:40 offset1:168
	s_waitcnt lgkmcnt(12)
	v_fmac_f32_e32 v37, v35, v36
	ds_write_b32 v179, v37 offset:41472
	ds_read2st64_b32 v[50:51], v179 offset0:41 offset1:169
	s_waitcnt lgkmcnt(12)
	v_fmac_f32_e32 v39, v37, v38
	ds_write_b32 v179, v39 offset:41728
	ds_read2st64_b32 v[52:53], v179 offset0:42 offset1:170
	s_waitcnt lgkmcnt(12)
	v_fmac_f32_e32 v41, v39, v40
	ds_write_b32 v179, v41 offset:41984
	ds_read2st64_b32 v[54:55], v179 offset0:43 offset1:171
	s_waitcnt lgkmcnt(12)
	v_fmac_f32_e32 v43, v41, v42
	ds_write_b32 v179, v43 offset:42240
	ds_read2st64_b32 v[56:57], v179 offset0:44 offset1:172
	s_waitcnt lgkmcnt(12)
	v_fmac_f32_e32 v45, v43, v44
	ds_write_b32 v179, v45 offset:42496
	ds_read2st64_b32 v[58:59], v179 offset0:45 offset1:173
	s_waitcnt lgkmcnt(12)
	v_fmac_f32_e32 v47, v45, v46
	ds_write_b32 v179, v47 offset:42752
	ds_read2st64_b32 v[60:61], v179 offset0:46 offset1:174
	s_waitcnt lgkmcnt(12)
	v_fmac_f32_e32 v49, v47, v48
	ds_write_b32 v179, v49 offset:43008
	ds_read2st64_b32 v[62:63], v179 offset0:47 offset1:175
	s_waitcnt lgkmcnt(12)
	v_fmac_f32_e32 v51, v49, v50
	ds_write_b32 v179, v51 offset:43264
	ds_read2st64_b32 v[32:33], v179 offset0:48 offset1:176
	s_waitcnt lgkmcnt(12)
	v_fmac_f32_e32 v53, v51, v52
	ds_write_b32 v179, v53 offset:43520
	ds_read2st64_b32 v[34:35], v179 offset0:49 offset1:177
	s_waitcnt lgkmcnt(12)
	v_fmac_f32_e32 v55, v53, v54
	ds_write_b32 v179, v55 offset:43776
	ds_read2st64_b32 v[36:37], v179 offset0:50 offset1:178
	s_waitcnt lgkmcnt(12)
	v_fmac_f32_e32 v57, v55, v56
	ds_write_b32 v179, v57 offset:44032
	ds_read2st64_b32 v[38:39], v179 offset0:51 offset1:179
	s_waitcnt lgkmcnt(12)
	v_fmac_f32_e32 v59, v57, v58
	ds_write_b32 v179, v59 offset:44288
	ds_read2st64_b32 v[40:41], v179 offset0:52 offset1:180
	s_waitcnt lgkmcnt(12)
	v_fmac_f32_e32 v61, v59, v60
	ds_write_b32 v179, v61 offset:44544
	ds_read2st64_b32 v[42:43], v179 offset0:53 offset1:181
	s_waitcnt lgkmcnt(12)
	v_fmac_f32_e32 v63, v61, v62
	ds_write_b32 v179, v63 offset:44800
	ds_read2st64_b32 v[44:45], v179 offset0:54 offset1:182
	s_waitcnt lgkmcnt(12)
	v_fmac_f32_e32 v33, v63, v32
	ds_write_b32 v179, v33 offset:45056
	ds_read2st64_b32 v[46:47], v179 offset0:55 offset1:183
	s_waitcnt lgkmcnt(12)
	v_fmac_f32_e32 v35, v33, v34
	ds_write_b32 v179, v35 offset:45312
	ds_read2st64_b32 v[48:49], v179 offset0:56 offset1:184
	s_waitcnt lgkmcnt(12)
	v_fmac_f32_e32 v37, v35, v36
	ds_write_b32 v179, v37 offset:45568
	ds_read2st64_b32 v[50:51], v179 offset0:57 offset1:185
	s_waitcnt lgkmcnt(12)
	v_fmac_f32_e32 v39, v37, v38
	ds_write_b32 v179, v39 offset:45824
	ds_read2st64_b32 v[52:53], v179 offset0:58 offset1:186
	s_waitcnt lgkmcnt(12)
	v_fmac_f32_e32 v41, v39, v40
	ds_write_b32 v179, v41 offset:46080
	ds_read2st64_b32 v[54:55], v179 offset0:59 offset1:187
	s_waitcnt lgkmcnt(12)
	v_fmac_f32_e32 v43, v41, v42
	ds_write_b32 v179, v43 offset:46336
	ds_read2st64_b32 v[56:57], v179 offset0:60 offset1:188
	s_waitcnt lgkmcnt(12)
	v_fmac_f32_e32 v45, v43, v44
	ds_write_b32 v179, v45 offset:46592
	ds_read2st64_b32 v[58:59], v179 offset0:61 offset1:189
	s_waitcnt lgkmcnt(12)
	v_fmac_f32_e32 v47, v45, v46
	ds_write_b32 v179, v47 offset:46848
	ds_read2st64_b32 v[60:61], v179 offset0:62 offset1:190
	s_waitcnt lgkmcnt(12)
	v_fmac_f32_e32 v49, v47, v48
	ds_write_b32 v179, v49 offset:47104
	ds_read2st64_b32 v[62:63], v179 offset0:63 offset1:191
	s_waitcnt lgkmcnt(12)
	v_fmac_f32_e32 v51, v49, v50
	ds_write_b32 v179, v51 offset:47360
	s_waitcnt lgkmcnt(11)
	v_fmac_f32_e32 v53, v51, v52
	ds_write_b32 v179, v53 offset:47616
	s_waitcnt lgkmcnt(10)
	v_fmac_f32_e32 v55, v53, v54
	ds_write_b32 v179, v55 offset:47872
	s_waitcnt lgkmcnt(9)
	v_fmac_f32_e32 v57, v55, v56
	ds_write_b32 v179, v57 offset:48128
	s_waitcnt lgkmcnt(8)
	v_fmac_f32_e32 v59, v57, v58
	ds_write_b32 v179, v59 offset:48384
	s_waitcnt lgkmcnt(7)
	v_fmac_f32_e32 v61, v59, v60
	ds_write_b32 v179, v61 offset:48640
	s_waitcnt lgkmcnt(6)
	v_fmac_f32_e32 v63, v61, v62
	ds_write_b32 v179, v63 offset:48896
	v_mov_b32_e32 v99, v63
	s_branch .LBB0_1073
.Llru_scan_bwd:
	ds_read2st64_b32 v[32:33], v179 offset0:63 offset1:191
	ds_read2st64_b32 v[34:35], v179 offset0:62 offset1:190
	ds_read2st64_b32 v[36:37], v179 offset0:61 offset1:189
	ds_read2st64_b32 v[38:39], v179 offset0:60 offset1:188
	ds_read2st64_b32 v[40:41], v179 offset0:59 offset1:187
	ds_read2st64_b32 v[42:43], v179 offset0:58 offset1:186
	ds_read2st64_b32 v[44:45], v179 offset0:57 offset1:185
	s_waitcnt lgkmcnt(6)
	v_fmac_f32_e32 v33, v99, v32
	ds_write_b32 v179, v33 offset:48896
	ds_read2st64_b32 v[46:47], v179 offset0:56 offset1:184
	s_waitcnt lgkmcnt(7)
	v_fmac_f32_e32 v35, v33, v34
	ds_write_b32 v179, v35 offset:48640
	ds_read2st64_b32 v[48:49], v179 offset0:55 offset1:183
	s_waitcnt lgkmcnt(8)
	v_fmac_f32_e32 v37, v35, v36
	ds_write_b32 v179, v37 offset:48384
	ds_read2st64_b32 v[50:51], v179 offset0:54 offset1:182
	s_waitcnt lgkmcnt(9)
	v_fmac_f32_e32 v39, v37, v38
	ds_write_b32 v179, v39 offset:48128
	ds_read2st64_b32 v[52:53], v179 offset0:53 offset1:181
	s_waitcnt lgkmcnt(10)
	v_fmac_f32_e32 v41, v39, v40
	ds_write_b32 v179, v41 offset:47872
	ds_read2st64_b32 v[54:55], v179 offset0:52 offset1:180
	s_waitcnt lgkmcnt(11)
	v_fmac_f32_e32 v43, v41, v42
	ds_write_b32 v179, v43 offset:47616
	ds_read2st64_b32 v[56:57], v179 offset0:51 offset1:179
	s_waitcnt lgkmcnt(12)
	v_fmac_f32_e32 v45, v43, v44
	ds_write_b32 v179, v45 offset:47360
	ds_read2st64_b32 v[58:59], v179 offset0:50 offset1:178
	s_waitcnt lgkmcnt(12)
	v_fmac_f32_e32 v47, v45, v46
	ds_write_b32 v179, v47 offset:47104
	ds_read2st64_b32 v[60:61], v179 offset0:49 offset1:177
	s_waitcnt lgkmcnt(12)
	v_fmac_f32_e32 v49, v47, v48
	ds_write_b32 v179, v49 offset:46848
	ds_read2st64_b32 v[62:63], v179 offset0:48 offset1:176
	s_waitcnt lgkmcnt(12)
	v_fmac_f32_e32 v51, v49, v50
	ds_write_b32 v179, v51 offset:46592
	ds_read2st64_b32 v[32:33], v179 offset0:47 offset1:175
	s_waitcnt lgkmcnt(12)
	v_fmac_f32_e32 v53, v51, v52
	ds_write_b32 v179, v53 offset:46336
	ds_read2st64_b32 v[34:35], v179 offset0:46 offset1:174
	s_waitcnt lgkmcnt(12)
	v_fmac_f32_e32 v55, v53, v54
	ds_write_b32 v179, v55 offset:46080
	ds_read2st64_b32 v[36:37], v179 offset0:45 offset1:173
	s_waitcnt lgkmcnt(12)
	v_fmac_f32_e32 v57, v55, v56
	ds_write_b32 v179, v57 offset:45824
	ds_read2st64_b32 v[38:39], v179 offset0:44 offset1:172
	s_waitcnt lgkmcnt(12)
	v_fmac_f32_e32 v59, v57, v58
	ds_write_b32 v179, v59 offset:45568
	ds_read2st64_b32 v[40:41], v179 offset0:43 offset1:171
	s_waitcnt lgkmcnt(12)
	v_fmac_f32_e32 v61, v59, v60
	ds_write_b32 v179, v61 offset:45312
	ds_read2st64_b32 v[42:43], v179 offset0:42 offset1:170
	s_waitcnt lgkmcnt(12)
	v_fmac_f32_e32 v63, v61, v62
	ds_write_b32 v179, v63 offset:45056
	ds_read2st64_b32 v[44:45], v179 offset0:41 offset1:169
	s_waitcnt lgkmcnt(12)
	v_fmac_f32_e32 v33, v63, v32
	ds_write_b32 v179, v33 offset:44800
	ds_read2st64_b32 v[46:47], v179 offset0:40 offset1:168
	s_waitcnt lgkmcnt(12)
	v_fmac_f32_e32 v35, v33, v34
	ds_write_b32 v179, v35 offset:44544
	ds_read2st64_b32 v[48:49], v179 offset0:39 offset1:167
	s_waitcnt lgkmcnt(12)
	v_fmac_f32_e32 v37, v35, v36
	ds_write_b32 v179, v37 offset:44288
	ds_read2st64_b32 v[50:51], v179 offset0:38 offset1:166
	s_waitcnt lgkmcnt(12)
	v_fmac_f32_e32 v39, v37, v38
	ds_write_b32 v179, v39 offset:44032
	ds_read2st64_b32 v[52:53], v179 offset0:37 offset1:165
	s_waitcnt lgkmcnt(12)
	v_fmac_f32_e32 v41, v39, v40
	ds_write_b32 v179, v41 offset:43776
	ds_read2st64_b32 v[54:55], v179 offset0:36 offset1:164
	s_waitcnt lgkmcnt(12)
	v_fmac_f32_e32 v43, v41, v42
	ds_write_b32 v179, v43 offset:43520
	ds_read2st64_b32 v[56:57], v179 offset0:35 offset1:163
	s_waitcnt lgkmcnt(12)
	v_fmac_f32_e32 v45, v43, v44
	ds_write_b32 v179, v45 offset:43264
	ds_read2st64_b32 v[58:59], v179 offset0:34 offset1:162
	s_waitcnt lgkmcnt(12)
	v_fmac_f32_e32 v47, v45, v46
	ds_write_b32 v179, v47 offset:43008
	ds_read2st64_b32 v[60:61], v179 offset0:33 offset1:161
	s_waitcnt lgkmcnt(12)
	v_fmac_f32_e32 v49, v47, v48
	ds_write_b32 v179, v49 offset:42752
	ds_read2st64_b32 v[62:63], v179 offset0:32 offset1:160
	s_waitcnt lgkmcnt(12)
	v_fmac_f32_e32 v51, v49, v50
	ds_write_b32 v179, v51 offset:42496
	ds_read2st64_b32 v[32:33], v179 offset0:31 offset1:159
	s_waitcnt lgkmcnt(12)
	v_fmac_f32_e32 v53, v51, v52
	ds_write_b32 v179, v53 offset:42240
	ds_read2st64_b32 v[34:35], v179 offset0:30 offset1:158
	s_waitcnt lgkmcnt(12)
	v_fmac_f32_e32 v55, v53, v54
	ds_write_b32 v179, v55 offset:41984
	ds_read2st64_b32 v[36:37], v179 offset0:29 offset1:157
	s_waitcnt lgkmcnt(12)
	v_fmac_f32_e32 v57, v55, v56
	ds_write_b32 v179, v57 offset:41728
	ds_read2st64_b32 v[38:39], v179 offset0:28 offset1:156
	s_waitcnt lgkmcnt(12)
	v_fmac_f32_e32 v59, v57, v58
	ds_write_b32 v179, v59 offset:41472
	ds_read2st64_b32 v[40:41], v179 offset0:27 offset1:155
	s_waitcnt lgkmcnt(12)
	v_fmac_f32_e32 v61, v59, v60
	ds_write_b32 v179, v61 offset:41216
	ds_read2st64_b32 v[42:43], v179 offset0:26 offset1:154
	s_waitcnt lgkmcnt(12)
	v_fmac_f32_e32 v63, v61, v62
	ds_write_b32 v179, v63 offset:40960
	ds_read2st64_b32 v[44:45], v179 offset0:25 offset1:153
	s_waitcnt lgkmcnt(12)
	v_fmac_f32_e32 v33, v63, v32
	ds_write_b32 v179, v33 offset:40704
	ds_read2st64_b32 v[46:47], v179 offset0:24 offset1:152
	s_waitcnt lgkmcnt(12)
	v_fmac_f32_e32 v35, v33, v34
	ds_write_b32 v179, v35 offset:40448
	ds_read2st64_b32 v[48:49], v179 offset0:23 offset1:151
	s_waitcnt lgkmcnt(12)
	v_fmac_f32_e32 v37, v35, v36
	ds_write_b32 v179, v37 offset:40192
	ds_read2st64_b32 v[50:51], v179 offset0:22 offset1:150
	s_waitcnt lgkmcnt(12)
	v_fmac_f32_e32 v39, v37, v38
	ds_write_b32 v179, v39 offset:39936
	ds_read2st64_b32 v[52:53], v179 offset0:21 offset1:149
	s_waitcnt lgkmcnt(12)
	v_fmac_f32_e32 v41, v39, v40
	ds_write_b32 v179, v41 offset:39680
	ds_read2st64_b32 v[54:55], v179 offset0:20 offset1:148
	s_waitcnt lgkmcnt(12)
	v_fmac_f32_e32 v43, v41, v42
	ds_write_b32 v179, v43 offset:39424
	ds_read2st64_b32 v[56:57], v179 offset0:19 offset1:147
	s_waitcnt lgkmcnt(12)
	v_fmac_f32_e32 v45, v43, v44
	ds_write_b32 v179, v45 offset:39168
	ds_read2st64_b32 v[58:59], v179 offset0:18 offset1:146
	s_waitcnt lgkmcnt(12)
	v_fmac_f32_e32 v47, v45, v46
	ds_write_b32 v179, v47 offset:38912
	ds_read2st64_b32 v[60:61], v179 offset0:17 offset1:145
	s_waitcnt lgkmcnt(12)
	v_fmac_f32_e32 v49, v47, v48
	ds_write_b32 v179, v49 offset:38656
	ds_read2st64_b32 v[62:63], v179 offset0:16 offset1:144
	s_waitcnt lgkmcnt(12)
	v_fmac_f32_e32 v51, v49, v50
	ds_write_b32 v179, v51 offset:38400
	ds_read2st64_b32 v[32:33], v179 offset0:15 offset1:143
	s_waitcnt lgkmcnt(12)
	v_fmac_f32_e32 v53, v51, v52
	ds_write_b32 v179, v53 offset:38144
	ds_read2st64_b32 v[34:35], v179 offset0:14 offset1:142
	s_waitcnt lgkmcnt(12)
	v_fmac_f32_e32 v55, v53, v54
	ds_write_b32 v179, v55 offset:37888
	ds_read2st64_b32 v[36:37], v179 offset0:13 offset1:141
	s_waitcnt lgkmcnt(12)
	v_fmac_f32_e32 v57, v55, v56
	ds_write_b32 v179, v57 offset:37632
	ds_read2st64_b32 v[38:39], v179 offset0:12 offset1:140
	s_waitcnt lgkmcnt(12)
	v_fmac_f32_e32 v59, v57, v58
	ds_write_b32 v179, v59 offset:37376
	ds_read2st64_b32 v[40:41], v179 offset0:11 offset1:139
	s_waitcnt lgkmcnt(12)
	v_fmac_f32_e32 v61, v59, v60
	ds_write_b32 v179, v61 offset:37120
	ds_read2st64_b32 v[42:43], v179 offset0:10 offset1:138
	s_waitcnt lgkmcnt(12)
	v_fmac_f32_e32 v63, v61, v62
	ds_write_b32 v179, v63 offset:36864
	ds_read2st64_b32 v[44:45], v179 offset0:9 offset1:137
	s_waitcnt lgkmcnt(12)
	v_fmac_f32_e32 v33, v63, v32
	ds_write_b32 v179, v33 offset:36608
	ds_read2st64_b32 v[46:47], v179 offset0:8 offset1:136
	s_waitcnt lgkmcnt(12)
	v_fmac_f32_e32 v35, v33, v34
	ds_write_b32 v179, v35 offset:36352
	ds_read2st64_b32 v[48:49], v179 offset0:7 offset1:135
	s_waitcnt lgkmcnt(12)
	v_fmac_f32_e32 v37, v35, v36
	ds_write_b32 v179, v37 offset:36096
	ds_read2st64_b32 v[50:51], v179 offset0:6 offset1:134
	s_waitcnt lgkmcnt(12)
	v_fmac_f32_e32 v39, v37, v38
	ds_write_b32 v179, v39 offset:35840
	ds_read2st64_b32 v[52:53], v179 offset0:5 offset1:133
	s_waitcnt lgkmcnt(12)
	v_fmac_f32_e32 v41, v39, v40
	ds_write_b32 v179, v41 offset:35584
	ds_read2st64_b32 v[54:55], v179 offset0:4 offset1:132
	s_waitcnt lgkmcnt(12)
	v_fmac_f32_e32 v43, v41, v42
	ds_write_b32 v179, v43 offset:35328
	ds_read2st64_b32 v[56:57], v179 offset0:3 offset1:131
	s_waitcnt lgkmcnt(12)
	v_fmac_f32_e32 v45, v43, v44
	ds_write_b32 v179, v45 offset:35072
	ds_read2st64_b32 v[58:59], v179 offset0:2 offset1:130
	s_waitcnt lgkmcnt(12)
	v_fmac_f32_e32 v47, v45, v46
	ds_write_b32 v179, v47 offset:34816
	ds_read2st64_b32 v[60:61], v179 offset0:1 offset1:129
	s_waitcnt lgkmcnt(12)
	v_fmac_f32_e32 v49, v47, v48
	ds_write_b32 v179, v49 offset:34560
	ds_read2st64_b32 v[62:63], v179 offset0:0 offset1:128
	s_waitcnt lgkmcnt(12)
	v_fmac_f32_e32 v51, v49, v50
	ds_write_b32 v179, v51 offset:34304
	s_waitcnt lgkmcnt(11)
	v_fmac_f32_e32 v53, v51, v52
	ds_write_b32 v179, v53 offset:34048
	s_waitcnt lgkmcnt(10)
	v_fmac_f32_e32 v55, v53, v54
	ds_write_b32 v179, v55 offset:33792
	s_waitcnt lgkmcnt(9)
	v_fmac_f32_e32 v57, v55, v56
	ds_write_b32 v179, v57 offset:33536
	s_waitcnt lgkmcnt(8)
	v_fmac_f32_e32 v59, v57, v58
	ds_write_b32 v179, v59 offset:33280
	s_waitcnt lgkmcnt(7)
	v_fmac_f32_e32 v61, v59, v60
	ds_write_b32 v179, v61 offset:33024
	s_waitcnt lgkmcnt(6)
	v_fmac_f32_e32 v63, v61, v62
	ds_write_b32 v179, v63 offset:32768
	v_mov_b32_e32 v99, v63
